# FoX / memory-attention item epilogue: both gate-tile load trips issued up front (counted waits)
# baseline (speedup 1.0000x reference)
; #define LAS __attribute__((address_space(3)))
; __device__ __forceinline__ float bflo(unsigned w) { return __uint_as_float(w << 16); }
; __device__ __forceinline__ float bfhi(unsigned w) { return __uint_as_float(w & 0xffff0000u); }
; __device__ __forceinline__ unsigned pk2(float lo, float hi) { const f32x2v v = {lo, hi}; return __builtin_bit_cast(unsigned, __builtin_convertvector(v, bf16x2v)); }
; __device__ __forceinline__ float silu_f(float g) { return g * fast_rcp(1.f + fast_exp2(-g * LOG2E)); }
; template <int MODE>
; __device__ __forceinline__ void attn_item(LAS unsigned char* lds, const AttnArgs& a, const int tid) {
;     ...
;         for (int i0 = 0; i0 < 8; i0 += 4) { u32x4 gv[4];
; #pragma unroll
;           for (int i = 0; i < 4; ++i) gv[i] = *(const u32x4*)(a.G + (size_t)(a.q0 + r0 + 32 * (i0 + i)) * a.ldg + 8 * ch);
; #pragma unroll
;           for (int i = 0; i < 4; ++i) *(LAS u32x4*)(lds + off_b(r0 + 32 * (i0 + i), ch)) = gv[i]; }
;         __syncthreads();
; #pragma unroll
;         for (int dt = 0; dt < 4; ++dt)
; #pragma unroll
;             for (int g = 0; g < 4; ++g) { const unsigned ad = off_b(lrow, 4 * dt + g) + 8u * hh;
;                 const u32x2 gw = *(const LAS u32x2*)(lds + ad);
;                 const float v0 = o[dt][4 * g + 0] * inv * silu_f(bflo(gw.x)), v1 = o[dt][4 * g + 1] * inv * silu_f(bfhi(gw.x));
;                 const float v2 = o[dt][4 * g + 2] * inv * silu_f(bflo(gw.y)), v3 = o[dt][4 * g + 3] * inv * silu_f(bfhi(gw.y));
;                 u32x2 w; w.x = pk2(v0, v1); w.y = pk2(v2, v3);
;                 *(LAS u32x2*)(lds + ad) = w; }
.LBB0_70:
	v_cndmask_b32_e64 v12, 0, 1, s[28:29]
	s_or_b32 s35, s34, 1
	v_cmp_ne_u32_e32 vcc, 1, v12
	v_lshl_add_u32 v12, s34, 5, v6
	s_or_b32 s36, s34, 2
	v_mad_i64_i32 v[12:13], s[28:29], v12, s38, v[4:5]
	v_lshl_add_u32 v80, s35, 5, v6
	s_or_b32 s37, s34, 3
	global_load_dwordx4 v[12:15], v[12:13], off offset:1024
	v_mad_i64_i32 v[80:81], s[28:29], v80, s38, v[4:5]
	v_lshl_add_u32 v84, s36, 5, v6
	global_load_dwordx4 v[80:83], v[80:81], off offset:1024
	v_mad_i64_i32 v[84:85], s[28:29], v84, s38, v[4:5]
	v_lshl_add_u32 v88, s37, 5, v6
	global_load_dwordx4 v[84:87], v[84:85], off offset:1024
	v_mad_i64_i32 v[88:89], s[28:29], v88, s38, v[4:5]
	global_load_dwordx4 v[88:91], v[88:89], off offset:1024
	s_mov_b32 s34, 4
	v_cndmask_b32_e64 v96, 0, 1, s[28:29]
	s_or_b32 s35, s34, 1
	v_cmp_ne_u32_e32 vcc, 1, v96
	v_lshl_add_u32 v96, s34, 5, v6
	s_or_b32 s36, s34, 2
	v_mad_i64_i32 v[96:97], s[28:29], v96, s38, v[4:5]
	v_lshl_add_u32 v100, s35, 5, v6
	s_or_b32 s37, s34, 3
	global_load_dwordx4 v[96:99], v[96:97], off offset:1024
	v_mad_i64_i32 v[100:101], s[28:29], v100, s38, v[4:5]
	v_lshl_add_u32 v104, s36, 5, v6
	global_load_dwordx4 v[100:103], v[100:101], off offset:1024
	v_mad_i64_i32 v[104:105], s[28:29], v104, s38, v[4:5]
	v_lshl_add_u32 v108, s37, 5, v6
	global_load_dwordx4 v[104:107], v[104:105], off offset:1024
	v_mad_i64_i32 v[108:109], s[28:29], v108, s38, v[4:5]
	global_load_dwordx4 v[108:111], v[108:109], off offset:1024
	s_mov_b64 s[28:29], 0
	s_waitcnt vmcnt(4) lgkmcnt(0)
	ds_write_b128 v11, v[12:15]
	v_add_u32_e32 v92, 0x2000, v11
	ds_write_b128 v92, v[80:83]
	v_add_u32_e32 v92, 0x4000, v11
	ds_write_b128 v92, v[84:87]
	v_add_u32_e32 v92, 0x6000, v11
	ds_write_b128 v92, v[88:91]
	s_waitcnt vmcnt(0)
	v_add_u32_e32 v92, 0x8000, v11
	ds_write_b128 v92, v[96:99]
	v_add_u32_e32 v92, 0xa000, v11
	ds_write_b128 v92, v[100:103]
	v_add_u32_e32 v92, 0xc000, v11
	ds_write_b128 v92, v[104:107]
	v_add_u32_e32 v92, 0xe000, v11
	ds_write_b128 v92, v[108:111]
	s_lshl_b64 s[18:19], s[18:19], 24
	s_add_u32 s18, s93, s18
	s_addc_u32 s19, s95, s19
	s_add_u32 s18, s18, s26
	v_add_f32_e32 v0, v154, v0
	s_addc_u32 s19, s19, s27
	v_div_scale_f32 v4, s[26:27], v0, v0, 1.0
	v_rcp_f32_e32 v5, v4
	s_waitcnt lgkmcnt(0)
	s_barrier
	v_fma_f32 v11, -v4, v5, 1.0
	v_fmac_f32_e32 v5, v11, v5
	v_div_scale_f32 v11, vcc, 1.0, v0, 1.0
	v_mul_f32_e32 v12, v11, v5
	v_fma_f32 v13, -v4, v12, v11
	v_fmac_f32_e32 v12, v13, v5
	v_fma_f32 v4, -v4, v12, v11
	v_div_fmas_f32 v4, v4, v5, v12
	v_div_fixup_f32 v0, v4, v0, 1.0
	v_lshlrev_b32_e32 v4, 8, v9
	v_lshlrev_b32_e32 v5, 2, v9
	v_bfe_u32 v9, v9, 2, 2
	v_and_or_b32 v5, v5, 12, v9
	v_lshlrev_b32_e32 v9, 3, v10
	v_add3_u32 v4, 0, v4, v9
	v_lshlrev_b32_e32 v5, 4, v5
	v_add_u32_e32 v9, v4, v5
	ds_read_b64 v[10:11], v9
	v_pk_mul_f32 v[64:65], v[64:65], v[0:1] op_sel_hi:[1,0]
	v_pk_mul_f32 v[48:49], v[48:49], v[0:1] op_sel_hi:[1,0]
	v_pk_mul_f32 v[32:33], v[32:33], v[0:1] op_sel_hi:[1,0]
	v_pk_mul_f32 v[16:17], v[16:17], v[0:1] op_sel_hi:[1,0]
	s_waitcnt lgkmcnt(0)
	v_lshlrev_b32_e32 v12, 16, v10
	v_and_b32_e32 v13, 0xffff0000, v10
	v_mul_f32_e32 v10, 0xbfb8aa3b, v12
	v_exp_f32_e32 v10, v10
	s_movk_i32 s26, 0xe0
	v_lshl_add_u64 v[2:3], v[2:3], 1, s[18:19]
	s_mov_b32 s18, 0
	v_add_f32_e32 v10, 1.0, v10
	v_rcp_f32_e32 v14, v10
	v_mul_f32_e32 v10, 0xbfb8aa3b, v13
	v_exp_f32_e32 v10, v10
	s_mov_b64 s[56:57], 0x100
	v_add_f32_e32 v10, 1.0, v10
	v_rcp_f32_e32 v15, v10
	v_lshlrev_b32_e32 v10, 16, v11
	v_and_b32_e32 v11, 0xffff0000, v11
	v_pk_mul_f32 v[12:13], v[14:15], v[12:13]
	v_mul_f32_e32 v14, 0xbfb8aa3b, v10
	v_mul_f32_e32 v15, 0xbfb8aa3b, v11
	v_exp_f32_e32 v14, v14
	v_exp_f32_e32 v15, v15
	v_pk_mul_f32 v[12:13], v[64:65], v[12:13]
	v_pk_mul_f32 v[64:65], v[66:67], v[0:1] op_sel_hi:[1,0]
	v_add_f32_e32 v14, 1.0, v14
	v_add_f32_e32 v15, 1.0, v15
	v_rcp_f32_e32 v14, v14
	v_rcp_f32_e32 v15, v15
	v_cvt_pk_bf16_f32 v12, v12, v13
	v_pk_mul_f32 v[10:11], v[14:15], v[10:11]
	s_nop 0
	v_pk_mul_f32 v[10:11], v[64:65], v[10:11]
	v_pk_mul_f32 v[64:65], v[68:69], v[0:1] op_sel_hi:[1,0]
	v_cvt_pk_bf16_f32 v13, v10, v11
	ds_write_b64 v9, v[12:13]
	v_xad_u32 v9, v5, 16, v4
	ds_read_b64 v[10:11], v9
	s_waitcnt lgkmcnt(0)
	v_lshlrev_b32_e32 v12, 16, v10
	v_and_b32_e32 v13, 0xffff0000, v10
	v_mul_f32_e32 v10, 0xbfb8aa3b, v12
	v_exp_f32_e32 v10, v10
	s_nop 0
	v_add_f32_e32 v10, 1.0, v10
	v_rcp_f32_e32 v14, v10
	v_mul_f32_e32 v10, 0xbfb8aa3b, v13
	v_exp_f32_e32 v10, v10
	s_nop 0
	v_add_f32_e32 v10, 1.0, v10
	v_rcp_f32_e32 v15, v10
	v_lshlrev_b32_e32 v10, 16, v11
	v_and_b32_e32 v11, 0xffff0000, v11
	v_pk_mul_f32 v[12:13], v[14:15], v[12:13]
	v_mul_f32_e32 v14, 0xbfb8aa3b, v10
	v_mul_f32_e32 v15, 0xbfb8aa3b, v11
	v_exp_f32_e32 v14, v14
	v_exp_f32_e32 v15, v15
	v_pk_mul_f32 v[12:13], v[64:65], v[12:13]
	v_pk_mul_f32 v[64:65], v[70:71], v[0:1] op_sel_hi:[1,0]
	v_add_f32_e32 v14, 1.0, v14
	v_add_f32_e32 v15, 1.0, v15
	v_rcp_f32_e32 v14, v14
	v_rcp_f32_e32 v15, v15
	v_cvt_pk_bf16_f32 v12, v12, v13
	v_pk_mul_f32 v[10:11], v[14:15], v[10:11]
	s_nop 0
	v_pk_mul_f32 v[10:11], v[64:65], v[10:11]
	v_pk_mul_f32 v[64:65], v[72:73], v[0:1] op_sel_hi:[1,0]
	v_cvt_pk_bf16_f32 v13, v10, v11
	ds_write_b64 v9, v[12:13]
	v_xad_u32 v9, v5, 32, v4
	ds_read_b64 v[10:11], v9
	s_waitcnt lgkmcnt(0)
; #define LAS __attribute__((address_space(3)))
; __device__ __forceinline__ float bflo(unsigned w) { return __uint_as_float(w << 16); }
; __device__ __forceinline__ float bfhi(unsigned w) { return __uint_as_float(w & 0xffff0000u); }
; __device__ __forceinline__ unsigned pk2(float lo, float hi) { const f32x2v v = {lo, hi}; return __builtin_bit_cast(unsigned, __builtin_convertvector(v, bf16x2v)); }
; __device__ __forceinline__ float silu_f(float g) { return g * fast_rcp(1.f + fast_exp2(-g * LOG2E)); }
; template <int MODE>
; __device__ __forceinline__ void attn_item(LAS unsigned char* lds, const AttnArgs& a, const int tid) {
;     ...
;         for (int dt = 0; dt < 4; ++dt)
; #pragma unroll
;             for (int g = 0; g < 4; ++g) { const unsigned ad = off_b(lrow, 4 * dt + g) + 8u * hh;
;                 const u32x2 gw = *(const LAS u32x2*)(lds + ad);
;                 const float v0 = o[dt][4 * g + 0] * inv * silu_f(bflo(gw.x)), v1 = o[dt][4 * g + 1] * inv * silu_f(bfhi(gw.x));
;                 const float v2 = o[dt][4 * g + 2] * inv * silu_f(bflo(gw.y)), v3 = o[dt][4 * g + 3] * inv * silu_f(bfhi(gw.y));
;                 u32x2 w; w.x = pk2(v0, v1); w.y = pk2(v2, v3);
;                 *(LAS u32x2*)(lds + ad) = w; }
;         __syncthreads();
	v_lshlrev_b32_e32 v12, 16, v10
	v_and_b32_e32 v13, 0xffff0000, v10
	v_mul_f32_e32 v10, 0xbfb8aa3b, v12
	v_exp_f32_e32 v10, v10
	s_nop 0
	v_add_f32_e32 v10, 1.0, v10
	v_rcp_f32_e32 v14, v10
	v_mul_f32_e32 v10, 0xbfb8aa3b, v13
	v_exp_f32_e32 v10, v10
	s_nop 0
	v_add_f32_e32 v10, 1.0, v10
	v_rcp_f32_e32 v15, v10
	v_lshlrev_b32_e32 v10, 16, v11
	v_and_b32_e32 v11, 0xffff0000, v11
	v_pk_mul_f32 v[12:13], v[14:15], v[12:13]
	v_mul_f32_e32 v14, 0xbfb8aa3b, v10
	v_mul_f32_e32 v15, 0xbfb8aa3b, v11
	v_exp_f32_e32 v14, v14
	v_exp_f32_e32 v15, v15
	v_pk_mul_f32 v[12:13], v[64:65], v[12:13]
	v_pk_mul_f32 v[64:65], v[74:75], v[0:1] op_sel_hi:[1,0]
	v_add_f32_e32 v14, 1.0, v14
	v_add_f32_e32 v15, 1.0, v15
	v_rcp_f32_e32 v14, v14
	v_rcp_f32_e32 v15, v15
	v_cvt_pk_bf16_f32 v12, v12, v13
	v_pk_mul_f32 v[10:11], v[14:15], v[10:11]
	s_nop 0
	v_pk_mul_f32 v[10:11], v[64:65], v[10:11]
	v_pk_mul_f32 v[64:65], v[76:77], v[0:1] op_sel_hi:[1,0]
	v_cvt_pk_bf16_f32 v13, v10, v11
	ds_write_b64 v9, v[12:13]
	v_xad_u32 v9, v5, 48, v4
	ds_read_b64 v[10:11], v9
	s_waitcnt lgkmcnt(0)
	v_lshlrev_b32_e32 v12, 16, v10
	v_and_b32_e32 v13, 0xffff0000, v10
	v_mul_f32_e32 v10, 0xbfb8aa3b, v12
	v_exp_f32_e32 v10, v10
	s_nop 0
	v_add_f32_e32 v10, 1.0, v10
	v_rcp_f32_e32 v14, v10
	v_mul_f32_e32 v10, 0xbfb8aa3b, v13
	v_exp_f32_e32 v10, v10
	s_nop 0
	v_add_f32_e32 v10, 1.0, v10
	v_rcp_f32_e32 v15, v10
	v_lshlrev_b32_e32 v10, 16, v11
	v_and_b32_e32 v11, 0xffff0000, v11
	v_pk_mul_f32 v[12:13], v[14:15], v[12:13]
	v_mul_f32_e32 v14, 0xbfb8aa3b, v10
	v_mul_f32_e32 v15, 0xbfb8aa3b, v11
	v_exp_f32_e32 v14, v14
	v_exp_f32_e32 v15, v15
	v_pk_mul_f32 v[12:13], v[64:65], v[12:13]
	v_pk_mul_f32 v[64:65], v[78:79], v[0:1] op_sel_hi:[1,0]
	v_add_f32_e32 v14, 1.0, v14
	v_add_f32_e32 v15, 1.0, v15
	v_rcp_f32_e32 v14, v14
	v_rcp_f32_e32 v15, v15
	v_cvt_pk_bf16_f32 v12, v12, v13
	v_pk_mul_f32 v[10:11], v[14:15], v[10:11]
	s_nop 0
	v_pk_mul_f32 v[10:11], v[64:65], v[10:11]
	s_nop 0
	v_cvt_pk_bf16_f32 v13, v10, v11
	ds_write_b64 v9, v[12:13]
	v_xad_u32 v9, v5, 64, v4
	ds_read_b64 v[10:11], v9
	s_waitcnt lgkmcnt(0)
	v_lshlrev_b32_e32 v12, 16, v10
	v_and_b32_e32 v13, 0xffff0000, v10
	v_mul_f32_e32 v10, 0xbfb8aa3b, v12
	v_exp_f32_e32 v10, v10
	s_nop 0
	v_add_f32_e32 v10, 1.0, v10
	v_rcp_f32_e32 v14, v10
	v_mul_f32_e32 v10, 0xbfb8aa3b, v13
	v_exp_f32_e32 v10, v10
	s_nop 0
	v_add_f32_e32 v10, 1.0, v10
	v_rcp_f32_e32 v15, v10
	v_lshlrev_b32_e32 v10, 16, v11
	v_and_b32_e32 v11, 0xffff0000, v11
	v_pk_mul_f32 v[12:13], v[14:15], v[12:13]
	v_mul_f32_e32 v14, 0xbfb8aa3b, v10
	v_mul_f32_e32 v15, 0xbfb8aa3b, v11
	v_exp_f32_e32 v14, v14
	v_exp_f32_e32 v15, v15
	v_pk_mul_f32 v[12:13], v[48:49], v[12:13]
	v_pk_mul_f32 v[48:49], v[50:51], v[0:1] op_sel_hi:[1,0]
	v_add_f32_e32 v14, 1.0, v14
	v_add_f32_e32 v15, 1.0, v15
	v_rcp_f32_e32 v14, v14
	v_rcp_f32_e32 v15, v15
	v_cvt_pk_bf16_f32 v12, v12, v13
	v_pk_mul_f32 v[10:11], v[14:15], v[10:11]
	s_nop 0
	v_pk_mul_f32 v[10:11], v[48:49], v[10:11]
	v_pk_mul_f32 v[48:49], v[52:53], v[0:1] op_sel_hi:[1,0]
	v_cvt_pk_bf16_f32 v13, v10, v11
	ds_write_b64 v9, v[12:13]
	v_xad_u32 v9, v5, s80, v4
	ds_read_b64 v[10:11], v9
	s_waitcnt lgkmcnt(0)
	v_lshlrev_b32_e32 v12, 16, v10
	v_and_b32_e32 v13, 0xffff0000, v10
	v_mul_f32_e32 v10, 0xbfb8aa3b, v12
	v_exp_f32_e32 v10, v10
	s_nop 0
	v_add_f32_e32 v10, 1.0, v10
	v_rcp_f32_e32 v14, v10
	v_mul_f32_e32 v10, 0xbfb8aa3b, v13
	v_exp_f32_e32 v10, v10
	s_nop 0
	v_add_f32_e32 v10, 1.0, v10
	v_rcp_f32_e32 v15, v10
	v_lshlrev_b32_e32 v10, 16, v11
	v_and_b32_e32 v11, 0xffff0000, v11
	v_pk_mul_f32 v[12:13], v[14:15], v[12:13]
	v_mul_f32_e32 v14, 0xbfb8aa3b, v10
	v_mul_f32_e32 v15, 0xbfb8aa3b, v11
	v_exp_f32_e32 v14, v14
	v_exp_f32_e32 v15, v15
	v_pk_mul_f32 v[12:13], v[48:49], v[12:13]
	v_pk_mul_f32 v[48:49], v[54:55], v[0:1] op_sel_hi:[1,0]
	v_add_f32_e32 v14, 1.0, v14
	v_add_f32_e32 v15, 1.0, v15
	v_rcp_f32_e32 v14, v14
	v_rcp_f32_e32 v15, v15
	v_cvt_pk_bf16_f32 v12, v12, v13
	v_pk_mul_f32 v[10:11], v[14:15], v[10:11]
	s_nop 0
	v_pk_mul_f32 v[10:11], v[48:49], v[10:11]
	v_pk_mul_f32 v[48:49], v[56:57], v[0:1] op_sel_hi:[1,0]
	v_cvt_pk_bf16_f32 v13, v10, v11
	ds_write_b64 v9, v[12:13]
	v_xad_u32 v9, v5, s79, v4
	ds_read_b64 v[10:11], v9
	s_waitcnt lgkmcnt(0)
	v_lshlrev_b32_e32 v12, 16, v10
	v_and_b32_e32 v13, 0xffff0000, v10
	v_mul_f32_e32 v10, 0xbfb8aa3b, v12
	v_exp_f32_e32 v10, v10
	s_nop 0
	v_add_f32_e32 v10, 1.0, v10
	v_rcp_f32_e32 v14, v10
	v_mul_f32_e32 v10, 0xbfb8aa3b, v13
	v_exp_f32_e32 v10, v10
	s_nop 0
	v_add_f32_e32 v10, 1.0, v10
	v_rcp_f32_e32 v15, v10
	v_lshlrev_b32_e32 v10, 16, v11
	v_and_b32_e32 v11, 0xffff0000, v11
	v_pk_mul_f32 v[12:13], v[14:15], v[12:13]
	v_mul_f32_e32 v14, 0xbfb8aa3b, v10
	v_mul_f32_e32 v15, 0xbfb8aa3b, v11
	v_exp_f32_e32 v14, v14
	v_exp_f32_e32 v15, v15
	v_pk_mul_f32 v[12:13], v[48:49], v[12:13]
	v_pk_mul_f32 v[48:49], v[58:59], v[0:1] op_sel_hi:[1,0]
	v_add_f32_e32 v14, 1.0, v14
	v_add_f32_e32 v15, 1.0, v15
	v_rcp_f32_e32 v14, v14
	v_rcp_f32_e32 v15, v15
	v_cvt_pk_bf16_f32 v12, v12, v13
	v_pk_mul_f32 v[10:11], v[14:15], v[10:11]
	s_nop 0
	v_pk_mul_f32 v[10:11], v[48:49], v[10:11]
	v_pk_mul_f32 v[48:49], v[60:61], v[0:1] op_sel_hi:[1,0]
	v_cvt_pk_bf16_f32 v13, v10, v11
	ds_write_b64 v9, v[12:13]
	v_xad_u32 v9, v5, s22, v4
	ds_read_b64 v[10:11], v9
	s_waitcnt lgkmcnt(0)
; #define LAS __attribute__((address_space(3)))
; __device__ __forceinline__ float bflo(unsigned w) { return __uint_as_float(w << 16); }
; __device__ __forceinline__ float bfhi(unsigned w) { return __uint_as_float(w & 0xffff0000u); }
; __device__ __forceinline__ unsigned pk2(float lo, float hi) { const f32x2v v = {lo, hi}; return __builtin_bit_cast(unsigned, __builtin_convertvector(v, bf16x2v)); }
; __device__ __forceinline__ float silu_f(float g) { return g * fast_rcp(1.f + fast_exp2(-g * LOG2E)); }
; template <int MODE>
; __device__ __forceinline__ void attn_item(LAS unsigned char* lds, const AttnArgs& a, const int tid) {
;     ...
;         for (int dt = 0; dt < 4; ++dt)
; #pragma unroll
;             for (int g = 0; g < 4; ++g) { const unsigned ad = off_b(lrow, 4 * dt + g) + 8u * hh;
;                 const u32x2 gw = *(const LAS u32x2*)(lds + ad);
;                 const float v0 = o[dt][4 * g + 0] * inv * silu_f(bflo(gw.x)), v1 = o[dt][4 * g + 1] * inv * silu_f(bfhi(gw.x));
;                 const float v2 = o[dt][4 * g + 2] * inv * silu_f(bflo(gw.y)), v3 = o[dt][4 * g + 3] * inv * silu_f(bfhi(gw.y));
;                 u32x2 w; w.x = pk2(v0, v1); w.y = pk2(v2, v3);
;                 *(LAS u32x2*)(lds + ad) = w; }
	v_lshlrev_b32_e32 v12, 16, v10
	v_and_b32_e32 v13, 0xffff0000, v10
	v_mul_f32_e32 v10, 0xbfb8aa3b, v12
	v_exp_f32_e32 v10, v10
	s_nop 0
	v_add_f32_e32 v10, 1.0, v10
	v_rcp_f32_e32 v14, v10
	v_mul_f32_e32 v10, 0xbfb8aa3b, v13
	v_exp_f32_e32 v10, v10
	s_nop 0
	v_add_f32_e32 v10, 1.0, v10
	v_rcp_f32_e32 v15, v10
	v_lshlrev_b32_e32 v10, 16, v11
	v_and_b32_e32 v11, 0xffff0000, v11
	v_pk_mul_f32 v[12:13], v[14:15], v[12:13]
	v_mul_f32_e32 v14, 0xbfb8aa3b, v10
	v_mul_f32_e32 v15, 0xbfb8aa3b, v11
	v_exp_f32_e32 v14, v14
	v_exp_f32_e32 v15, v15
	v_pk_mul_f32 v[12:13], v[48:49], v[12:13]
	v_pk_mul_f32 v[48:49], v[62:63], v[0:1] op_sel_hi:[1,0]
	v_add_f32_e32 v14, 1.0, v14
	v_add_f32_e32 v15, 1.0, v15
	v_rcp_f32_e32 v14, v14
	v_rcp_f32_e32 v15, v15
	v_cvt_pk_bf16_f32 v12, v12, v13
	v_pk_mul_f32 v[10:11], v[14:15], v[10:11]
	s_nop 0
	v_pk_mul_f32 v[10:11], v[48:49], v[10:11]
	s_nop 0
	v_cvt_pk_bf16_f32 v13, v10, v11
	ds_write_b64 v9, v[12:13]
	v_xad_u32 v9, v5, s24, v4
	ds_read_b64 v[10:11], v9
	s_waitcnt lgkmcnt(0)
	v_lshlrev_b32_e32 v12, 16, v10
	v_and_b32_e32 v13, 0xffff0000, v10
	v_mul_f32_e32 v10, 0xbfb8aa3b, v12
	v_exp_f32_e32 v10, v10
	s_nop 0
	v_add_f32_e32 v10, 1.0, v10
	v_rcp_f32_e32 v14, v10
	v_mul_f32_e32 v10, 0xbfb8aa3b, v13
	v_exp_f32_e32 v10, v10
	s_nop 0
	v_add_f32_e32 v10, 1.0, v10
	v_rcp_f32_e32 v15, v10
	v_lshlrev_b32_e32 v10, 16, v11
	v_and_b32_e32 v11, 0xffff0000, v11
	v_pk_mul_f32 v[12:13], v[14:15], v[12:13]
	v_mul_f32_e32 v14, 0xbfb8aa3b, v10
	v_mul_f32_e32 v15, 0xbfb8aa3b, v11
	v_exp_f32_e32 v14, v14
	v_exp_f32_e32 v15, v15
	v_pk_mul_f32 v[12:13], v[32:33], v[12:13]
	v_pk_mul_f32 v[32:33], v[34:35], v[0:1] op_sel_hi:[1,0]
	v_add_f32_e32 v14, 1.0, v14
	v_add_f32_e32 v15, 1.0, v15
	v_rcp_f32_e32 v14, v14
	v_rcp_f32_e32 v15, v15
	v_cvt_pk_bf16_f32 v12, v12, v13
	v_pk_mul_f32 v[10:11], v[14:15], v[10:11]
	s_nop 0
	v_pk_mul_f32 v[10:11], v[32:33], v[10:11]
	v_pk_mul_f32 v[32:33], v[36:37], v[0:1] op_sel_hi:[1,0]
	v_cvt_pk_bf16_f32 v13, v10, v11
	ds_write_b64 v9, v[12:13]
	v_xad_u32 v9, v5, s25, v4
	ds_read_b64 v[10:11], v9
	s_waitcnt lgkmcnt(0)
	v_lshlrev_b32_e32 v12, 16, v10
	v_and_b32_e32 v13, 0xffff0000, v10
	v_mul_f32_e32 v10, 0xbfb8aa3b, v12
	v_exp_f32_e32 v10, v10
	s_nop 0
	v_add_f32_e32 v10, 1.0, v10
	v_rcp_f32_e32 v14, v10
	v_mul_f32_e32 v10, 0xbfb8aa3b, v13
	v_exp_f32_e32 v10, v10
	s_nop 0
	v_add_f32_e32 v10, 1.0, v10
	v_rcp_f32_e32 v15, v10
	v_lshlrev_b32_e32 v10, 16, v11
	v_and_b32_e32 v11, 0xffff0000, v11
	v_pk_mul_f32 v[12:13], v[14:15], v[12:13]
	v_mul_f32_e32 v14, 0xbfb8aa3b, v10
	v_mul_f32_e32 v15, 0xbfb8aa3b, v11
	v_exp_f32_e32 v14, v14
	v_exp_f32_e32 v15, v15
	v_pk_mul_f32 v[12:13], v[32:33], v[12:13]
	v_pk_mul_f32 v[32:33], v[38:39], v[0:1] op_sel_hi:[1,0]
	v_add_f32_e32 v14, 1.0, v14
	v_add_f32_e32 v15, 1.0, v15
	v_rcp_f32_e32 v14, v14
	v_rcp_f32_e32 v15, v15
	v_cvt_pk_bf16_f32 v12, v12, v13
	v_pk_mul_f32 v[10:11], v[14:15], v[10:11]
	s_nop 0
	v_pk_mul_f32 v[10:11], v[32:33], v[10:11]
	v_pk_mul_f32 v[32:33], v[40:41], v[0:1] op_sel_hi:[1,0]
	v_cvt_pk_bf16_f32 v13, v10, v11
	ds_write_b64 v9, v[12:13]
	v_xad_u32 v9, v5, s75, v4
	ds_read_b64 v[10:11], v9
	s_waitcnt lgkmcnt(0)
	v_lshlrev_b32_e32 v12, 16, v10
	v_and_b32_e32 v13, 0xffff0000, v10
	v_mul_f32_e32 v10, 0xbfb8aa3b, v12
	v_exp_f32_e32 v10, v10
	s_nop 0
	v_add_f32_e32 v10, 1.0, v10
	v_rcp_f32_e32 v14, v10
	v_mul_f32_e32 v10, 0xbfb8aa3b, v13
	v_exp_f32_e32 v10, v10
	s_nop 0
	v_add_f32_e32 v10, 1.0, v10
	v_rcp_f32_e32 v15, v10
	v_lshlrev_b32_e32 v10, 16, v11
	v_and_b32_e32 v11, 0xffff0000, v11
	v_pk_mul_f32 v[12:13], v[14:15], v[12:13]
	v_mul_f32_e32 v14, 0xbfb8aa3b, v10
	v_mul_f32_e32 v15, 0xbfb8aa3b, v11
	v_exp_f32_e32 v14, v14
	v_exp_f32_e32 v15, v15
	v_pk_mul_f32 v[12:13], v[32:33], v[12:13]
	v_pk_mul_f32 v[32:33], v[42:43], v[0:1] op_sel_hi:[1,0]
	v_add_f32_e32 v14, 1.0, v14
	v_add_f32_e32 v15, 1.0, v15
	v_rcp_f32_e32 v14, v14
	v_rcp_f32_e32 v15, v15
	v_cvt_pk_bf16_f32 v12, v12, v13
	v_pk_mul_f32 v[10:11], v[14:15], v[10:11]
	s_nop 0
	v_pk_mul_f32 v[10:11], v[32:33], v[10:11]
	v_pk_mul_f32 v[32:33], v[44:45], v[0:1] op_sel_hi:[1,0]
	v_cvt_pk_bf16_f32 v13, v10, v11
	ds_write_b64 v9, v[12:13]
	v_xad_u32 v9, v5, s76, v4
	ds_read_b64 v[10:11], v9
	s_waitcnt lgkmcnt(0)
; #define LAS __attribute__((address_space(3)))
; __device__ __forceinline__ float bflo(unsigned w) { return __uint_as_float(w << 16); }
; __device__ __forceinline__ float bfhi(unsigned w) { return __uint_as_float(w & 0xffff0000u); }
; __device__ __forceinline__ unsigned pk2(float lo, float hi) { const f32x2v v = {lo, hi}; return __builtin_bit_cast(unsigned, __builtin_convertvector(v, bf16x2v)); }
; __device__ __forceinline__ float silu_f(float g) { return g * fast_rcp(1.f + fast_exp2(-g * LOG2E)); }
; template <int MODE>
; __device__ __forceinline__ void attn_item(LAS unsigned char* lds, const AttnArgs& a, const int tid) {
;     ...
;         for (int dt = 0; dt < 4; ++dt)
; #pragma unroll
;             for (int g = 0; g < 4; ++g) { const unsigned ad = off_b(lrow, 4 * dt + g) + 8u * hh;
;                 const u32x2 gw = *(const LAS u32x2*)(lds + ad);
;                 const float v0 = o[dt][4 * g + 0] * inv * silu_f(bflo(gw.x)), v1 = o[dt][4 * g + 1] * inv * silu_f(bfhi(gw.x));
;                 const float v2 = o[dt][4 * g + 2] * inv * silu_f(bflo(gw.y)), v3 = o[dt][4 * g + 3] * inv * silu_f(bfhi(gw.y));
;                 u32x2 w; w.x = pk2(v0, v1); w.y = pk2(v2, v3);
;                 *(LAS u32x2*)(lds + ad) = w; }
;         __syncthreads();
	v_lshlrev_b32_e32 v12, 16, v10
	v_and_b32_e32 v13, 0xffff0000, v10
	v_mul_f32_e32 v10, 0xbfb8aa3b, v12
	v_exp_f32_e32 v10, v10
	s_nop 0
	v_add_f32_e32 v10, 1.0, v10
	v_rcp_f32_e32 v14, v10
	v_mul_f32_e32 v10, 0xbfb8aa3b, v13
	v_exp_f32_e32 v10, v10
	s_nop 0
	v_add_f32_e32 v10, 1.0, v10
	v_rcp_f32_e32 v15, v10
	v_lshlrev_b32_e32 v10, 16, v11
	v_and_b32_e32 v11, 0xffff0000, v11
	v_pk_mul_f32 v[12:13], v[14:15], v[12:13]
	v_mul_f32_e32 v14, 0xbfb8aa3b, v10
	v_mul_f32_e32 v15, 0xbfb8aa3b, v11
	v_exp_f32_e32 v14, v14
	v_exp_f32_e32 v15, v15
	v_pk_mul_f32 v[12:13], v[32:33], v[12:13]
	v_pk_mul_f32 v[32:33], v[46:47], v[0:1] op_sel_hi:[1,0]
	v_add_f32_e32 v14, 1.0, v14
	v_add_f32_e32 v15, 1.0, v15
	v_rcp_f32_e32 v14, v14
	v_rcp_f32_e32 v15, v15
	v_cvt_pk_bf16_f32 v12, v12, v13
	v_pk_mul_f32 v[10:11], v[14:15], v[10:11]
	s_nop 0
	v_pk_mul_f32 v[10:11], v[32:33], v[10:11]
	s_nop 0
	v_cvt_pk_bf16_f32 v13, v10, v11
	ds_write_b64 v9, v[12:13]
	v_xad_u32 v9, v5, s77, v4
	ds_read_b64 v[10:11], v9
	s_waitcnt lgkmcnt(0)
	v_lshlrev_b32_e32 v12, 16, v10
	v_and_b32_e32 v13, 0xffff0000, v10
	v_mul_f32_e32 v10, 0xbfb8aa3b, v12
	v_exp_f32_e32 v10, v10
	s_nop 0
	v_add_f32_e32 v10, 1.0, v10
	v_rcp_f32_e32 v14, v10
	v_mul_f32_e32 v10, 0xbfb8aa3b, v13
	v_exp_f32_e32 v10, v10
	s_nop 0
	v_add_f32_e32 v10, 1.0, v10
	v_rcp_f32_e32 v15, v10
	v_lshlrev_b32_e32 v10, 16, v11
	v_and_b32_e32 v11, 0xffff0000, v11
	v_pk_mul_f32 v[12:13], v[14:15], v[12:13]
	v_mul_f32_e32 v14, 0xbfb8aa3b, v10
	v_mul_f32_e32 v15, 0xbfb8aa3b, v11
	v_exp_f32_e32 v14, v14
	v_exp_f32_e32 v15, v15
	v_pk_mul_f32 v[12:13], v[16:17], v[12:13]
	v_pk_mul_f32 v[16:17], v[18:19], v[0:1] op_sel_hi:[1,0]
	v_add_f32_e32 v14, 1.0, v14
	v_add_f32_e32 v15, 1.0, v15
	v_rcp_f32_e32 v14, v14
	v_rcp_f32_e32 v15, v15
	v_cvt_pk_bf16_f32 v12, v12, v13
	v_pk_mul_f32 v[10:11], v[14:15], v[10:11]
	s_nop 0
	v_pk_mul_f32 v[10:11], v[16:17], v[10:11]
	v_pk_mul_f32 v[16:17], v[20:21], v[0:1] op_sel_hi:[1,0]
	v_cvt_pk_bf16_f32 v13, v10, v11
	ds_write_b64 v9, v[12:13]
	v_xad_u32 v9, v5, s78, v4
	ds_read_b64 v[10:11], v9
	s_waitcnt lgkmcnt(0)
	v_lshlrev_b32_e32 v12, 16, v10
	v_and_b32_e32 v13, 0xffff0000, v10
	v_mul_f32_e32 v10, 0xbfb8aa3b, v12
	v_exp_f32_e32 v10, v10
	s_nop 0
	v_add_f32_e32 v10, 1.0, v10
	v_rcp_f32_e32 v14, v10
	v_mul_f32_e32 v10, 0xbfb8aa3b, v13
	v_exp_f32_e32 v10, v10
	s_nop 0
	v_add_f32_e32 v10, 1.0, v10
	v_rcp_f32_e32 v15, v10
	v_lshlrev_b32_e32 v10, 16, v11
	v_and_b32_e32 v11, 0xffff0000, v11
	v_pk_mul_f32 v[12:13], v[14:15], v[12:13]
	v_mul_f32_e32 v14, 0xbfb8aa3b, v10
	v_mul_f32_e32 v15, 0xbfb8aa3b, v11
	v_exp_f32_e32 v14, v14
	v_exp_f32_e32 v15, v15
	v_pk_mul_f32 v[12:13], v[16:17], v[12:13]
	v_pk_mul_f32 v[16:17], v[22:23], v[0:1] op_sel_hi:[1,0]
	v_add_f32_e32 v14, 1.0, v14
	v_add_f32_e32 v15, 1.0, v15
	v_rcp_f32_e32 v14, v14
	v_rcp_f32_e32 v15, v15
	v_cvt_pk_bf16_f32 v12, v12, v13
	v_pk_mul_f32 v[10:11], v[14:15], v[10:11]
	s_nop 0
	v_pk_mul_f32 v[10:11], v[16:17], v[10:11]
	v_pk_mul_f32 v[16:17], v[24:25], v[0:1] op_sel_hi:[1,0]
	v_cvt_pk_bf16_f32 v13, v10, v11
	ds_write_b64 v9, v[12:13]
	v_xad_u32 v9, v5, s26, v4
	ds_read_b64 v[10:11], v9
	s_movk_i32 s26, 0xf0
	s_waitcnt lgkmcnt(0)
	v_lshlrev_b32_e32 v12, 16, v10
	v_and_b32_e32 v13, 0xffff0000, v10
	v_mul_f32_e32 v10, 0xbfb8aa3b, v12
	v_exp_f32_e32 v10, v10
	s_nop 0
	v_add_f32_e32 v10, 1.0, v10
	v_rcp_f32_e32 v14, v10
	v_mul_f32_e32 v10, 0xbfb8aa3b, v13
	v_exp_f32_e32 v10, v10
	s_nop 0
	v_add_f32_e32 v10, 1.0, v10
	v_rcp_f32_e32 v15, v10
	v_lshlrev_b32_e32 v10, 16, v11
	v_and_b32_e32 v11, 0xffff0000, v11
	v_pk_mul_f32 v[12:13], v[14:15], v[12:13]
	v_mul_f32_e32 v14, 0xbfb8aa3b, v10
	v_mul_f32_e32 v15, 0xbfb8aa3b, v11
	v_exp_f32_e32 v14, v14
	v_exp_f32_e32 v15, v15
	v_pk_mul_f32 v[12:13], v[16:17], v[12:13]
	v_pk_mul_f32 v[16:17], v[26:27], v[0:1] op_sel_hi:[1,0]
	v_add_f32_e32 v14, 1.0, v14
	v_add_f32_e32 v15, 1.0, v15
	v_rcp_f32_e32 v14, v14
	v_rcp_f32_e32 v15, v15
	v_cvt_pk_bf16_f32 v12, v12, v13
	v_pk_mul_f32 v[10:11], v[14:15], v[10:11]
	s_nop 0
	v_pk_mul_f32 v[10:11], v[16:17], v[10:11]
	v_pk_mul_f32 v[14:15], v[28:29], v[0:1] op_sel_hi:[1,0]
	v_cvt_pk_bf16_f32 v13, v10, v11
	ds_write_b64 v9, v[12:13]
	v_xad_u32 v9, v5, s26, v4
	ds_read_b64 v[4:5], v9
	s_waitcnt lgkmcnt(0)
	v_lshlrev_b32_e32 v10, 16, v4
	v_and_b32_e32 v11, 0xffff0000, v4
	v_mul_f32_e32 v4, 0xbfb8aa3b, v10
	v_exp_f32_e32 v4, v4
	s_nop 0
	v_add_f32_e32 v4, 1.0, v4
	v_rcp_f32_e32 v12, v4
	v_mul_f32_e32 v4, 0xbfb8aa3b, v11
	v_exp_f32_e32 v4, v4
	s_nop 0
	v_add_f32_e32 v4, 1.0, v4
	v_rcp_f32_e32 v13, v4
	v_lshlrev_b32_e32 v4, 16, v5
	v_and_b32_e32 v5, 0xffff0000, v5
	v_pk_mul_f32 v[10:11], v[12:13], v[10:11]
	s_nop 0
	v_pk_mul_f32 v[10:11], v[14:15], v[10:11]
	v_mul_f32_e32 v12, 0xbfb8aa3b, v4
	v_pk_mul_f32 v[14:15], v[30:31], v[0:1] op_sel_hi:[1,0]
	v_mul_f32_e32 v0, 0xbfb8aa3b, v5
	v_exp_f32_e32 v12, v12
	v_exp_f32_e32 v0, v0
	v_cvt_pk_bf16_f32 v10, v10, v11
	v_add_f32_e32 v12, 1.0, v12
	v_add_f32_e32 v0, 1.0, v0
	v_rcp_f32_e32 v12, v12
	v_rcp_f32_e32 v13, v0
	v_add3_u32 v0, v7, v8, 0
	v_pk_mul_f32 v[4:5], v[12:13], v[4:5]
	s_nop 0
	v_pk_mul_f32 v[4:5], v[14:15], v[4:5]
	s_nop 0
	v_cvt_pk_bf16_f32 v11, v4, v5
	ds_write_b64 v9, v[10:11]
	s_waitcnt lgkmcnt(0)
	s_barrier

; #define LAS __attribute__((address_space(3)))
; __device__ __forceinline__ float bflo(unsigned w) { return __uint_as_float(w << 16); }
; __device__ __forceinline__ float bfhi(unsigned w) { return __uint_as_float(w & 0xffff0000u); }
; __device__ __forceinline__ unsigned pk2(float lo, float hi) { const f32x2v v = {lo, hi}; return __builtin_bit_cast(unsigned, __builtin_convertvector(v, bf16x2v)); }
; __device__ __forceinline__ float silu_f(float g) { return g * fast_rcp(1.f + fast_exp2(-g * LOG2E)); }
; template <int MODE>
; __device__ __forceinline__ void attn_item(LAS unsigned char* lds, const AttnArgs& a, const int tid) {
;     ...
;         for (int i0 = 0; i0 < 8; i0 += 4) { u32x4 gv[4];
; #pragma unroll
;           for (int i = 0; i < 4; ++i) gv[i] = *(const u32x4*)(a.G + (size_t)(a.q0 + r0 + 32 * (i0 + i)) * a.ldg + 8 * ch);
; #pragma unroll
;           for (int i = 0; i < 4; ++i) *(LAS u32x4*)(lds + off_b(r0 + 32 * (i0 + i), ch)) = gv[i]; }
;         __syncthreads();
; #pragma unroll
;         for (int dt = 0; dt < 4; ++dt)
; #pragma unroll
;             for (int g = 0; g < 4; ++g) { const unsigned ad = off_b(lrow, 4 * dt + g) + 8u * hh;
;                 const u32x2 gw = *(const LAS u32x2*)(lds + ad);
;                 const float v0 = o[dt][4 * g + 0] * inv * silu_f(bflo(gw.x)), v1 = o[dt][4 * g + 1] * inv * silu_f(bfhi(gw.x));
;                 const float v2 = o[dt][4 * g + 2] * inv * silu_f(bflo(gw.y)), v3 = o[dt][4 * g + 3] * inv * silu_f(bfhi(gw.y));
;                 u32x2 w; w.x = pk2(v0, v1); w.y = pk2(v2, v3);
;                 *(LAS u32x2*)(lds + ad) = w; }
.LBB0_99:
	v_cndmask_b32_e64 v78, 0, 1, s[6:7]
	s_or_b32 s10, s9, 1
	v_cmp_ne_u32_e32 vcc, 1, v78
	v_lshl_add_u32 v78, s9, 5, v77
	s_or_b32 s11, s9, 2
	v_mad_i64_i32 v[78:79], s[6:7], v78, s67, 0
	v_lshl_add_u32 v82, s10, 5, v77
	s_or_b32 s19, s9, 3
	v_lshl_add_u64 v[78:79], v[78:79], 1, v[68:69]
	v_mad_i64_i32 v[82:83], s[6:7], v82, s67, 0
	v_lshl_add_u32 v86, s11, 5, v77
	global_load_dwordx4 v[78:81], v[78:79], off offset:3072
	v_lshl_add_u64 v[82:83], v[82:83], 1, v[68:69]
	v_mad_i64_i32 v[86:87], s[6:7], v86, s67, 0
	v_lshl_add_u32 v90, s19, 5, v77
	global_load_dwordx4 v[82:85], v[82:83], off offset:3072
	v_lshl_add_u64 v[86:87], v[86:87], 1, v[68:69]
	v_mad_i64_i32 v[90:91], s[6:7], v90, s67, 0
	global_load_dwordx4 v[86:89], v[86:87], off offset:3072
	v_lshl_add_u64 v[90:91], v[90:91], 1, v[68:69]
	global_load_dwordx4 v[90:93], v[90:91], off offset:3072
	s_mov_b32 s9, 4
	v_cndmask_b32_e64 v102, 0, 1, s[6:7]
	s_or_b32 s10, s9, 1
	v_cmp_ne_u32_e32 vcc, 1, v102
	v_lshl_add_u32 v102, s9, 5, v77
	s_or_b32 s11, s9, 2
	v_mad_i64_i32 v[102:103], s[6:7], v102, s67, 0
	v_lshl_add_u32 v106, s10, 5, v77
	s_or_b32 s19, s9, 3
	v_lshl_add_u64 v[102:103], v[102:103], 1, v[68:69]
	v_mad_i64_i32 v[106:107], s[6:7], v106, s67, 0
	v_lshl_add_u32 v110, s11, 5, v77
	global_load_dwordx4 v[102:105], v[102:103], off offset:3072
	v_lshl_add_u64 v[106:107], v[106:107], 1, v[68:69]
	v_mad_i64_i32 v[110:111], s[6:7], v110, s67, 0
	v_lshl_add_u32 v114, s19, 5, v77
	global_load_dwordx4 v[106:109], v[106:107], off offset:3072
	v_lshl_add_u64 v[110:111], v[110:111], 1, v[68:69]
	v_mad_i64_i32 v[114:115], s[6:7], v114, s67, 0
	global_load_dwordx4 v[110:113], v[110:111], off offset:3072
	v_lshl_add_u64 v[114:115], v[114:115], 1, v[68:69]
	global_load_dwordx4 v[114:117], v[114:115], off offset:3072
	s_mov_b64 s[6:7], 0
	s_waitcnt vmcnt(4) lgkmcnt(0)
	ds_write_b128 v76, v[78:81]
	v_add_u32_e32 v94, 0x2000, v76
	ds_write_b128 v94, v[82:85]
	v_add_u32_e32 v94, 0x4000, v76
	ds_write_b128 v94, v[86:89]
	v_add_u32_e32 v94, 0x6000, v76
	ds_write_b128 v94, v[90:93]
	s_waitcnt vmcnt(0)
	v_add_u32_e32 v94, 0x8000, v76
	ds_write_b128 v94, v[102:105]
	v_add_u32_e32 v94, 0xa000, v76
	ds_write_b128 v94, v[106:109]
	v_add_u32_e32 v94, 0xc000, v76
	ds_write_b128 v94, v[110:113]
	v_add_u32_e32 v94, 0xe000, v76
	ds_write_b128 v94, v[114:117]
	s_and_b32 s6, s17, 0xf00
	s_lshl_b64 s[4:5], s[4:5], 24
	s_add_u32 s4, s93, s4
	s_addc_u32 s5, s95, s5
	v_add_f32_e32 v68, v140, v75
	s_add_u32 s4, s4, s8
	v_div_scale_f32 v69, s[8:9], v68, v68, 1.0
	v_rcp_f32_e32 v75, v69
	v_lshlrev_b32_e32 v74, 3, v74
	s_waitcnt lgkmcnt(0)
	s_barrier
	v_fma_f32 v76, -v69, v75, 1.0
	v_fmac_f32_e32 v75, v76, v75
	v_div_scale_f32 v76, vcc, 1.0, v68, 1.0
	v_mul_f32_e32 v77, v76, v75
	v_fma_f32 v78, -v69, v77, v76
	v_fmac_f32_e32 v77, v78, v75
	v_fma_f32 v69, -v69, v77, v76
	v_div_fmas_f32 v69, v69, v75, v77
	v_div_fixup_f32 v68, v69, v68, 1.0
	v_lshlrev_b32_e32 v69, 8, v73
	v_lshlrev_b32_e32 v75, 2, v73
	v_bfe_u32 v73, v73, 2, 2
	v_and_or_b32 v73, v75, 12, v73
	v_add3_u32 v69, 0, v69, v74
	v_lshlrev_b32_e32 v73, 4, v73
	v_add_u32_e32 v80, v69, v73
	ds_read_b64 v[74:75], v80
	v_pk_mul_f32 v[50:51], v[50:51], v[68:69] op_sel_hi:[1,0]
	v_pk_mul_f32 v[52:53], v[52:53], v[68:69] op_sel_hi:[1,0]
	v_pk_mul_f32 v[54:55], v[54:55], v[68:69] op_sel_hi:[1,0]
	v_pk_mul_f32 v[56:57], v[56:57], v[68:69] op_sel_hi:[1,0]
	s_waitcnt lgkmcnt(0)
	v_lshlrev_b32_e32 v76, 16, v74
	v_and_b32_e32 v77, 0xffff0000, v74
	v_mul_f32_e32 v74, 0xbfb8aa3b, v76
	v_exp_f32_e32 v74, v74
	v_pk_mul_f32 v[34:35], v[34:35], v[68:69] op_sel_hi:[1,0]
	v_pk_mul_f32 v[36:37], v[36:37], v[68:69] op_sel_hi:[1,0]
	v_pk_mul_f32 v[38:39], v[38:39], v[68:69] op_sel_hi:[1,0]
	v_add_f32_e32 v74, 1.0, v74
	v_rcp_f32_e32 v78, v74
	v_mul_f32_e32 v74, 0xbfb8aa3b, v77
	v_exp_f32_e32 v74, v74
	v_pk_mul_f32 v[40:41], v[40:41], v[68:69] op_sel_hi:[1,0]
	v_pk_mul_f32 v[18:19], v[18:19], v[68:69] op_sel_hi:[1,0]
	v_pk_mul_f32 v[20:21], v[20:21], v[68:69] op_sel_hi:[1,0]
	v_add_f32_e32 v74, 1.0, v74
	v_rcp_f32_e32 v79, v74
	v_lshlrev_b32_e32 v74, 16, v75
	v_and_b32_e32 v75, 0xffff0000, v75
	v_pk_mul_f32 v[22:23], v[22:23], v[68:69] op_sel_hi:[1,0]
	v_pk_mul_f32 v[76:77], v[78:79], v[76:77]
	v_pk_mul_f32 v[24:25], v[24:25], v[68:69] op_sel_hi:[1,0]
	v_pk_mul_f32 v[50:51], v[50:51], v[76:77]
	v_mul_f32_e32 v76, 0xbfb8aa3b, v74
	v_mul_f32_e32 v77, 0xbfb8aa3b, v75
	v_exp_f32_e32 v76, v76
	v_exp_f32_e32 v77, v77
	v_cvt_pk_bf16_f32 v50, v50, v51
	v_pk_mul_f32 v[2:3], v[2:3], v[68:69] op_sel_hi:[1,0]
	v_add_f32_e32 v76, 1.0, v76
	v_add_f32_e32 v77, 1.0, v77
	v_rcp_f32_e32 v76, v76
	v_rcp_f32_e32 v77, v77
	v_pk_mul_f32 v[4:5], v[4:5], v[68:69] op_sel_hi:[1,0]
	v_pk_mul_f32 v[6:7], v[6:7], v[68:69] op_sel_hi:[1,0]
	v_pk_mul_f32 v[8:9], v[8:9], v[68:69] op_sel_hi:[1,0]
	v_pk_mul_f32 v[74:75], v[76:77], v[74:75]
	v_xad_u32 v76, v73, 16, v69
	v_pk_mul_f32 v[52:53], v[52:53], v[74:75]
	s_movk_i32 s7, 0xe0
	v_cvt_pk_bf16_f32 v51, v52, v53
	ds_write_b64 v80, v[50:51]
	ds_read_b64 v[50:51], v76
	s_addc_u32 s5, s5, 0
	s_waitcnt lgkmcnt(0)
	v_lshlrev_b32_e32 v52, 16, v50
	v_and_b32_e32 v53, 0xffff0000, v50
	v_mul_f32_e32 v50, 0xbfb8aa3b, v52
	v_exp_f32_e32 v50, v50
	s_nop 0
	v_add_f32_e32 v50, 1.0, v50
	v_rcp_f32_e32 v74, v50
	v_mul_f32_e32 v50, 0xbfb8aa3b, v53
	v_exp_f32_e32 v50, v50
	s_nop 0
	v_add_f32_e32 v50, 1.0, v50
	v_rcp_f32_e32 v75, v50
	v_lshlrev_b32_e32 v50, 16, v51
	v_and_b32_e32 v51, 0xffff0000, v51
	v_pk_mul_f32 v[52:53], v[74:75], v[52:53]
	s_nop 0
	v_pk_mul_f32 v[52:53], v[54:55], v[52:53]
	v_mul_f32_e32 v54, 0xbfb8aa3b, v50
	v_mul_f32_e32 v55, 0xbfb8aa3b, v51
	v_exp_f32_e32 v54, v54
	v_exp_f32_e32 v55, v55
	v_cvt_pk_bf16_f32 v52, v52, v53
	v_xad_u32 v74, v73, 32, v69
	v_add_f32_e32 v54, 1.0, v54
	v_add_f32_e32 v55, 1.0, v55
	v_rcp_f32_e32 v54, v54
	v_rcp_f32_e32 v55, v55
	s_nop 0
	v_pk_mul_f32 v[50:51], v[54:55], v[50:51]
	s_nop 0
	v_pk_mul_f32 v[50:51], v[56:57], v[50:51]
	v_pk_mul_f32 v[56:57], v[58:59], v[68:69] op_sel_hi:[1,0]
	v_cvt_pk_bf16_f32 v53, v50, v51
	ds_write_b64 v76, v[52:53]
	ds_read_b64 v[50:51], v74
	v_xad_u32 v58, v73, 48, v69
	s_waitcnt lgkmcnt(0)
; #define LAS __attribute__((address_space(3)))
; __device__ __forceinline__ float bflo(unsigned w) { return __uint_as_float(w << 16); }
; __device__ __forceinline__ float bfhi(unsigned w) { return __uint_as_float(w & 0xffff0000u); }
; __device__ __forceinline__ unsigned pk2(float lo, float hi) { const f32x2v v = {lo, hi}; return __builtin_bit_cast(unsigned, __builtin_convertvector(v, bf16x2v)); }
; __device__ __forceinline__ float silu_f(float g) { return g * fast_rcp(1.f + fast_exp2(-g * LOG2E)); }
; template <int MODE>
; __device__ __forceinline__ void attn_item(LAS unsigned char* lds, const AttnArgs& a, const int tid) {
;     ...
;         for (int dt = 0; dt < 4; ++dt)
; #pragma unroll
;             for (int g = 0; g < 4; ++g) { const unsigned ad = off_b(lrow, 4 * dt + g) + 8u * hh;
;                 const u32x2 gw = *(const LAS u32x2*)(lds + ad);
;                 const float v0 = o[dt][4 * g + 0] * inv * silu_f(bflo(gw.x)), v1 = o[dt][4 * g + 1] * inv * silu_f(bfhi(gw.x));
;                 const float v2 = o[dt][4 * g + 2] * inv * silu_f(bflo(gw.y)), v3 = o[dt][4 * g + 3] * inv * silu_f(bfhi(gw.y));
;                 u32x2 w; w.x = pk2(v0, v1); w.y = pk2(v2, v3);
;                 *(LAS u32x2*)(lds + ad) = w; }
	v_lshlrev_b32_e32 v52, 16, v50
	v_and_b32_e32 v53, 0xffff0000, v50
	v_mul_f32_e32 v50, 0xbfb8aa3b, v52
	v_exp_f32_e32 v50, v50
	s_nop 0
	v_add_f32_e32 v50, 1.0, v50
	v_rcp_f32_e32 v54, v50
	v_mul_f32_e32 v50, 0xbfb8aa3b, v53
	v_exp_f32_e32 v50, v50
	s_nop 0
	v_add_f32_e32 v50, 1.0, v50
	v_rcp_f32_e32 v55, v50
	v_lshlrev_b32_e32 v50, 16, v51
	v_and_b32_e32 v51, 0xffff0000, v51
	v_pk_mul_f32 v[52:53], v[54:55], v[52:53]
	v_mul_f32_e32 v54, 0xbfb8aa3b, v50
	v_mul_f32_e32 v55, 0xbfb8aa3b, v51
	v_exp_f32_e32 v54, v54
	v_exp_f32_e32 v55, v55
	v_pk_mul_f32 v[52:53], v[56:57], v[52:53]
	v_pk_mul_f32 v[56:57], v[60:61], v[68:69] op_sel_hi:[1,0]
	v_add_f32_e32 v54, 1.0, v54
	v_add_f32_e32 v55, 1.0, v55
	v_rcp_f32_e32 v54, v54
	v_rcp_f32_e32 v55, v55
	v_cvt_pk_bf16_f32 v52, v52, v53
	v_pk_mul_f32 v[50:51], v[54:55], v[50:51]
	s_nop 0
	v_pk_mul_f32 v[50:51], v[56:57], v[50:51]
	v_pk_mul_f32 v[56:57], v[62:63], v[68:69] op_sel_hi:[1,0]
	v_cvt_pk_bf16_f32 v53, v50, v51
	ds_write_b64 v74, v[52:53]
	ds_read_b64 v[50:51], v58
	s_waitcnt lgkmcnt(0)
	v_lshlrev_b32_e32 v52, 16, v50
	v_and_b32_e32 v53, 0xffff0000, v50
	v_mul_f32_e32 v50, 0xbfb8aa3b, v52
	v_exp_f32_e32 v50, v50
	s_nop 0
	v_add_f32_e32 v50, 1.0, v50
	v_rcp_f32_e32 v54, v50
	v_mul_f32_e32 v50, 0xbfb8aa3b, v53
	v_exp_f32_e32 v50, v50
	s_nop 0
	v_add_f32_e32 v50, 1.0, v50
	v_rcp_f32_e32 v55, v50
	v_lshlrev_b32_e32 v50, 16, v51
	v_and_b32_e32 v51, 0xffff0000, v51
	v_pk_mul_f32 v[52:53], v[54:55], v[52:53]
	v_mul_f32_e32 v54, 0xbfb8aa3b, v50
	v_mul_f32_e32 v55, 0xbfb8aa3b, v51
	v_exp_f32_e32 v54, v54
	v_exp_f32_e32 v55, v55
	v_pk_mul_f32 v[52:53], v[56:57], v[52:53]
	v_pk_mul_f32 v[56:57], v[64:65], v[68:69] op_sel_hi:[1,0]
	v_add_f32_e32 v54, 1.0, v54
	v_add_f32_e32 v55, 1.0, v55
	v_rcp_f32_e32 v54, v54
	v_rcp_f32_e32 v55, v55
	v_cvt_pk_bf16_f32 v52, v52, v53
	v_pk_mul_f32 v[50:51], v[54:55], v[50:51]
	s_nop 0
	v_pk_mul_f32 v[50:51], v[56:57], v[50:51]
	v_xad_u32 v56, v73, 64, v69
	v_cvt_pk_bf16_f32 v53, v50, v51
	ds_write_b64 v58, v[52:53]
	ds_read_b64 v[50:51], v56
	s_waitcnt lgkmcnt(0)
	v_lshlrev_b32_e32 v52, 16, v50
	v_and_b32_e32 v53, 0xffff0000, v50
	v_mul_f32_e32 v50, 0xbfb8aa3b, v52
	v_exp_f32_e32 v50, v50
	s_nop 0
	v_add_f32_e32 v50, 1.0, v50
	v_rcp_f32_e32 v54, v50
	v_mul_f32_e32 v50, 0xbfb8aa3b, v53
	v_exp_f32_e32 v50, v50
	s_nop 0
	v_add_f32_e32 v50, 1.0, v50
	v_rcp_f32_e32 v55, v50
	v_lshlrev_b32_e32 v50, 16, v51
	v_and_b32_e32 v51, 0xffff0000, v51
	v_pk_mul_f32 v[52:53], v[54:55], v[52:53]
	s_nop 0
	v_pk_mul_f32 v[34:35], v[34:35], v[52:53]
	v_mul_f32_e32 v52, 0xbfb8aa3b, v50
	v_mul_f32_e32 v53, 0xbfb8aa3b, v51
	v_exp_f32_e32 v52, v52
	v_exp_f32_e32 v53, v53
	v_cvt_pk_bf16_f32 v34, v34, v35
	v_add_f32_e32 v52, 1.0, v52
	v_add_f32_e32 v53, 1.0, v53
	v_rcp_f32_e32 v52, v52
	v_rcp_f32_e32 v53, v53
	s_nop 0
	v_pk_mul_f32 v[50:51], v[52:53], v[50:51]
	s_nop 0
	v_pk_mul_f32 v[36:37], v[36:37], v[50:51]
	v_xad_u32 v52, v73, s80, v69
	v_cvt_pk_bf16_f32 v35, v36, v37
	ds_write_b64 v56, v[34:35]
	ds_read_b64 v[34:35], v52
	s_waitcnt lgkmcnt(0)
	v_lshlrev_b32_e32 v36, 16, v34
	v_and_b32_e32 v37, 0xffff0000, v34
	v_mul_f32_e32 v34, 0xbfb8aa3b, v36
	v_exp_f32_e32 v34, v34
	s_nop 0
	v_add_f32_e32 v34, 1.0, v34
	v_rcp_f32_e32 v50, v34
	v_mul_f32_e32 v34, 0xbfb8aa3b, v37
	v_exp_f32_e32 v34, v34
	s_nop 0
	v_add_f32_e32 v34, 1.0, v34
	v_rcp_f32_e32 v51, v34
	v_lshlrev_b32_e32 v34, 16, v35
	v_and_b32_e32 v35, 0xffff0000, v35
	v_pk_mul_f32 v[36:37], v[50:51], v[36:37]
	s_nop 0
	v_pk_mul_f32 v[36:37], v[38:39], v[36:37]
	v_mul_f32_e32 v38, 0xbfb8aa3b, v34
	v_mul_f32_e32 v39, 0xbfb8aa3b, v35
	v_exp_f32_e32 v38, v38
	v_exp_f32_e32 v39, v39
	v_cvt_pk_bf16_f32 v36, v36, v37
	v_xad_u32 v50, v73, s79, v69
	v_add_f32_e32 v38, 1.0, v38
	v_add_f32_e32 v39, 1.0, v39
	v_rcp_f32_e32 v38, v38
	v_rcp_f32_e32 v39, v39
	s_nop 0
	v_pk_mul_f32 v[34:35], v[38:39], v[34:35]
	s_nop 0
	v_pk_mul_f32 v[34:35], v[40:41], v[34:35]
	v_pk_mul_f32 v[40:41], v[42:43], v[68:69] op_sel_hi:[1,0]
	v_cvt_pk_bf16_f32 v37, v34, v35
	ds_write_b64 v52, v[36:37]
	ds_read_b64 v[34:35], v50
	v_xad_u32 v42, v73, s22, v69
	s_waitcnt lgkmcnt(0)
	v_lshlrev_b32_e32 v36, 16, v34
	v_and_b32_e32 v37, 0xffff0000, v34
	v_mul_f32_e32 v34, 0xbfb8aa3b, v36
	v_exp_f32_e32 v34, v34
	s_nop 0
	v_add_f32_e32 v34, 1.0, v34
	v_rcp_f32_e32 v38, v34
	v_mul_f32_e32 v34, 0xbfb8aa3b, v37
	v_exp_f32_e32 v34, v34
	s_nop 0
	v_add_f32_e32 v34, 1.0, v34
	v_rcp_f32_e32 v39, v34
	v_lshlrev_b32_e32 v34, 16, v35
	v_and_b32_e32 v35, 0xffff0000, v35
	v_pk_mul_f32 v[36:37], v[38:39], v[36:37]
	v_mul_f32_e32 v38, 0xbfb8aa3b, v34
	v_mul_f32_e32 v39, 0xbfb8aa3b, v35
	v_exp_f32_e32 v38, v38
	v_exp_f32_e32 v39, v39
	v_pk_mul_f32 v[36:37], v[40:41], v[36:37]
	v_pk_mul_f32 v[40:41], v[44:45], v[68:69] op_sel_hi:[1,0]
	v_add_f32_e32 v38, 1.0, v38
	v_add_f32_e32 v39, 1.0, v39
	v_rcp_f32_e32 v38, v38
	v_rcp_f32_e32 v39, v39
	v_cvt_pk_bf16_f32 v36, v36, v37
	v_pk_mul_f32 v[34:35], v[38:39], v[34:35]
	s_nop 0
	v_pk_mul_f32 v[34:35], v[40:41], v[34:35]
	v_pk_mul_f32 v[40:41], v[46:47], v[68:69] op_sel_hi:[1,0]
	v_cvt_pk_bf16_f32 v37, v34, v35
	ds_write_b64 v50, v[36:37]
	ds_read_b64 v[34:35], v42
	s_waitcnt lgkmcnt(0)
; #define LAS __attribute__((address_space(3)))
; __device__ __forceinline__ float bflo(unsigned w) { return __uint_as_float(w << 16); }
; __device__ __forceinline__ float bfhi(unsigned w) { return __uint_as_float(w & 0xffff0000u); }
; __device__ __forceinline__ unsigned pk2(float lo, float hi) { const f32x2v v = {lo, hi}; return __builtin_bit_cast(unsigned, __builtin_convertvector(v, bf16x2v)); }
; __device__ __forceinline__ float silu_f(float g) { return g * fast_rcp(1.f + fast_exp2(-g * LOG2E)); }
; template <int MODE>
; __device__ __forceinline__ void attn_item(LAS unsigned char* lds, const AttnArgs& a, const int tid) {
;     ...
;         for (int dt = 0; dt < 4; ++dt)
; #pragma unroll
;             for (int g = 0; g < 4; ++g) { const unsigned ad = off_b(lrow, 4 * dt + g) + 8u * hh;
;                 const u32x2 gw = *(const LAS u32x2*)(lds + ad);
;                 const float v0 = o[dt][4 * g + 0] * inv * silu_f(bflo(gw.x)), v1 = o[dt][4 * g + 1] * inv * silu_f(bfhi(gw.x));
;                 const float v2 = o[dt][4 * g + 2] * inv * silu_f(bflo(gw.y)), v3 = o[dt][4 * g + 3] * inv * silu_f(bfhi(gw.y));
;                 u32x2 w; w.x = pk2(v0, v1); w.y = pk2(v2, v3);
;                 *(LAS u32x2*)(lds + ad) = w; }
	v_lshlrev_b32_e32 v36, 16, v34
	v_and_b32_e32 v37, 0xffff0000, v34
	v_mul_f32_e32 v34, 0xbfb8aa3b, v36
	v_exp_f32_e32 v34, v34
	s_nop 0
	v_add_f32_e32 v34, 1.0, v34
	v_rcp_f32_e32 v38, v34
	v_mul_f32_e32 v34, 0xbfb8aa3b, v37
	v_exp_f32_e32 v34, v34
	s_nop 0
	v_add_f32_e32 v34, 1.0, v34
	v_rcp_f32_e32 v39, v34
	v_lshlrev_b32_e32 v34, 16, v35
	v_and_b32_e32 v35, 0xffff0000, v35
	v_pk_mul_f32 v[36:37], v[38:39], v[36:37]
	v_mul_f32_e32 v38, 0xbfb8aa3b, v34
	v_mul_f32_e32 v39, 0xbfb8aa3b, v35
	v_exp_f32_e32 v38, v38
	v_exp_f32_e32 v39, v39
	v_pk_mul_f32 v[36:37], v[40:41], v[36:37]
	v_pk_mul_f32 v[40:41], v[48:49], v[68:69] op_sel_hi:[1,0]
	v_add_f32_e32 v38, 1.0, v38
	v_add_f32_e32 v39, 1.0, v39
	v_rcp_f32_e32 v38, v38
	v_rcp_f32_e32 v39, v39
	v_cvt_pk_bf16_f32 v36, v36, v37
	v_pk_mul_f32 v[34:35], v[38:39], v[34:35]
	s_nop 0
	v_pk_mul_f32 v[34:35], v[40:41], v[34:35]
	v_xad_u32 v40, v73, s24, v69
	v_cvt_pk_bf16_f32 v37, v34, v35
	ds_write_b64 v42, v[36:37]
	ds_read_b64 v[34:35], v40
	s_waitcnt lgkmcnt(0)
	v_lshlrev_b32_e32 v36, 16, v34
	v_and_b32_e32 v37, 0xffff0000, v34
	v_mul_f32_e32 v34, 0xbfb8aa3b, v36
	v_exp_f32_e32 v34, v34
	s_nop 0
	v_add_f32_e32 v34, 1.0, v34
	v_rcp_f32_e32 v38, v34
	v_mul_f32_e32 v34, 0xbfb8aa3b, v37
	v_exp_f32_e32 v34, v34
	s_nop 0
	v_add_f32_e32 v34, 1.0, v34
	v_rcp_f32_e32 v39, v34
	v_lshlrev_b32_e32 v34, 16, v35
	v_and_b32_e32 v35, 0xffff0000, v35
	v_pk_mul_f32 v[36:37], v[38:39], v[36:37]
	s_nop 0
	v_pk_mul_f32 v[18:19], v[18:19], v[36:37]
	v_mul_f32_e32 v36, 0xbfb8aa3b, v34
	v_mul_f32_e32 v37, 0xbfb8aa3b, v35
	v_exp_f32_e32 v36, v36
	v_exp_f32_e32 v37, v37
	v_cvt_pk_bf16_f32 v18, v18, v19
	v_add_f32_e32 v36, 1.0, v36
	v_add_f32_e32 v37, 1.0, v37
	v_rcp_f32_e32 v36, v36
	v_rcp_f32_e32 v37, v37
	s_nop 0
	v_pk_mul_f32 v[34:35], v[36:37], v[34:35]
	s_nop 0
	v_pk_mul_f32 v[20:21], v[20:21], v[34:35]
	v_xad_u32 v36, v73, s25, v69
	v_cvt_pk_bf16_f32 v19, v20, v21
	ds_write_b64 v40, v[18:19]
	ds_read_b64 v[18:19], v36
	s_waitcnt lgkmcnt(0)
	v_lshlrev_b32_e32 v20, 16, v18
	v_and_b32_e32 v21, 0xffff0000, v18
	v_mul_f32_e32 v18, 0xbfb8aa3b, v20
	v_exp_f32_e32 v18, v18
	s_nop 0
	v_add_f32_e32 v18, 1.0, v18
	v_rcp_f32_e32 v34, v18
	v_mul_f32_e32 v18, 0xbfb8aa3b, v21
	v_exp_f32_e32 v18, v18
	s_nop 0
	v_add_f32_e32 v18, 1.0, v18
	v_rcp_f32_e32 v35, v18
	v_lshlrev_b32_e32 v18, 16, v19
	v_and_b32_e32 v19, 0xffff0000, v19
	v_pk_mul_f32 v[20:21], v[34:35], v[20:21]
	s_nop 0
	v_pk_mul_f32 v[20:21], v[22:23], v[20:21]
	v_mul_f32_e32 v22, 0xbfb8aa3b, v18
	v_mul_f32_e32 v23, 0xbfb8aa3b, v19
	v_exp_f32_e32 v22, v22
	v_exp_f32_e32 v23, v23
	v_cvt_pk_bf16_f32 v20, v20, v21
	v_xad_u32 v34, v73, s75, v69
	v_add_f32_e32 v22, 1.0, v22
	v_add_f32_e32 v23, 1.0, v23
	v_rcp_f32_e32 v22, v22
	v_rcp_f32_e32 v23, v23
	s_nop 0
	v_pk_mul_f32 v[18:19], v[22:23], v[18:19]
	s_nop 0
	v_pk_mul_f32 v[18:19], v[24:25], v[18:19]
	v_pk_mul_f32 v[24:25], v[26:27], v[68:69] op_sel_hi:[1,0]
	v_cvt_pk_bf16_f32 v21, v18, v19
	ds_write_b64 v36, v[20:21]
	ds_read_b64 v[18:19], v34
	v_xad_u32 v26, v73, s76, v69
	s_waitcnt lgkmcnt(0)
	v_lshlrev_b32_e32 v20, 16, v18
	v_and_b32_e32 v21, 0xffff0000, v18
	v_mul_f32_e32 v18, 0xbfb8aa3b, v20
	v_exp_f32_e32 v18, v18
	s_nop 0
	v_add_f32_e32 v18, 1.0, v18
	v_rcp_f32_e32 v22, v18
	v_mul_f32_e32 v18, 0xbfb8aa3b, v21
	v_exp_f32_e32 v18, v18
	s_nop 0
	v_add_f32_e32 v18, 1.0, v18
	v_rcp_f32_e32 v23, v18
	v_lshlrev_b32_e32 v18, 16, v19
	v_and_b32_e32 v19, 0xffff0000, v19
	v_pk_mul_f32 v[20:21], v[22:23], v[20:21]
	v_mul_f32_e32 v22, 0xbfb8aa3b, v18
	v_mul_f32_e32 v23, 0xbfb8aa3b, v19
	v_exp_f32_e32 v22, v22
	v_exp_f32_e32 v23, v23
	v_pk_mul_f32 v[20:21], v[24:25], v[20:21]
	v_pk_mul_f32 v[24:25], v[28:29], v[68:69] op_sel_hi:[1,0]
	v_add_f32_e32 v22, 1.0, v22
	v_add_f32_e32 v23, 1.0, v23
	v_rcp_f32_e32 v22, v22
	v_rcp_f32_e32 v23, v23
	v_cvt_pk_bf16_f32 v20, v20, v21
	v_pk_mul_f32 v[18:19], v[22:23], v[18:19]
	s_nop 0
	v_pk_mul_f32 v[18:19], v[24:25], v[18:19]
	v_pk_mul_f32 v[24:25], v[30:31], v[68:69] op_sel_hi:[1,0]
	v_cvt_pk_bf16_f32 v21, v18, v19
	ds_write_b64 v34, v[20:21]
	ds_read_b64 v[18:19], v26
	s_waitcnt lgkmcnt(0)
; #define LAS __attribute__((address_space(3)))
; __device__ __forceinline__ float bflo(unsigned w) { return __uint_as_float(w << 16); }
; __device__ __forceinline__ float bfhi(unsigned w) { return __uint_as_float(w & 0xffff0000u); }
; __device__ __forceinline__ unsigned pk2(float lo, float hi) { const f32x2v v = {lo, hi}; return __builtin_bit_cast(unsigned, __builtin_convertvector(v, bf16x2v)); }
; __device__ __forceinline__ float silu_f(float g) { return g * fast_rcp(1.f + fast_exp2(-g * LOG2E)); }
; template <int MODE>
; __device__ __forceinline__ void attn_item(LAS unsigned char* lds, const AttnArgs& a, const int tid) {
;     ...
;         for (int dt = 0; dt < 4; ++dt)
; #pragma unroll
;             for (int g = 0; g < 4; ++g) { const unsigned ad = off_b(lrow, 4 * dt + g) + 8u * hh;
;                 const u32x2 gw = *(const LAS u32x2*)(lds + ad);
;                 const float v0 = o[dt][4 * g + 0] * inv * silu_f(bflo(gw.x)), v1 = o[dt][4 * g + 1] * inv * silu_f(bfhi(gw.x));
;                 const float v2 = o[dt][4 * g + 2] * inv * silu_f(bflo(gw.y)), v3 = o[dt][4 * g + 3] * inv * silu_f(bfhi(gw.y));
;                 u32x2 w; w.x = pk2(v0, v1); w.y = pk2(v2, v3);
;                 *(LAS u32x2*)(lds + ad) = w; }
;         __syncthreads();
	v_lshlrev_b32_e32 v20, 16, v18
	v_and_b32_e32 v21, 0xffff0000, v18
	v_mul_f32_e32 v18, 0xbfb8aa3b, v20
	v_exp_f32_e32 v18, v18
	s_nop 0
	v_add_f32_e32 v18, 1.0, v18
	v_rcp_f32_e32 v22, v18
	v_mul_f32_e32 v18, 0xbfb8aa3b, v21
	v_exp_f32_e32 v18, v18
	s_nop 0
	v_add_f32_e32 v18, 1.0, v18
	v_rcp_f32_e32 v23, v18
	v_lshlrev_b32_e32 v18, 16, v19
	v_and_b32_e32 v19, 0xffff0000, v19
	v_pk_mul_f32 v[20:21], v[22:23], v[20:21]
	v_mul_f32_e32 v22, 0xbfb8aa3b, v18
	v_mul_f32_e32 v23, 0xbfb8aa3b, v19
	v_exp_f32_e32 v22, v22
	v_exp_f32_e32 v23, v23
	v_pk_mul_f32 v[20:21], v[24:25], v[20:21]
	v_pk_mul_f32 v[24:25], v[32:33], v[68:69] op_sel_hi:[1,0]
	v_add_f32_e32 v22, 1.0, v22
	v_add_f32_e32 v23, 1.0, v23
	v_rcp_f32_e32 v22, v22
	v_rcp_f32_e32 v23, v23
	v_cvt_pk_bf16_f32 v20, v20, v21
	v_pk_mul_f32 v[18:19], v[22:23], v[18:19]
	s_nop 0
	v_pk_mul_f32 v[18:19], v[24:25], v[18:19]
	v_xad_u32 v24, v73, s77, v69
	v_cvt_pk_bf16_f32 v21, v18, v19
	ds_write_b64 v26, v[20:21]
	ds_read_b64 v[18:19], v24
	s_waitcnt lgkmcnt(0)
	v_lshlrev_b32_e32 v20, 16, v18
	v_and_b32_e32 v21, 0xffff0000, v18
	v_mul_f32_e32 v18, 0xbfb8aa3b, v20
	v_exp_f32_e32 v18, v18
	s_nop 0
	v_add_f32_e32 v18, 1.0, v18
	v_rcp_f32_e32 v22, v18
	v_mul_f32_e32 v18, 0xbfb8aa3b, v21
	v_exp_f32_e32 v18, v18
	s_nop 0
	v_add_f32_e32 v18, 1.0, v18
	v_rcp_f32_e32 v23, v18
	v_lshlrev_b32_e32 v18, 16, v19
	v_and_b32_e32 v19, 0xffff0000, v19
	v_pk_mul_f32 v[20:21], v[22:23], v[20:21]
	s_nop 0
	v_pk_mul_f32 v[2:3], v[2:3], v[20:21]
	v_mul_f32_e32 v20, 0xbfb8aa3b, v18
	v_mul_f32_e32 v21, 0xbfb8aa3b, v19
	v_exp_f32_e32 v20, v20
	v_exp_f32_e32 v21, v21
	v_cvt_pk_bf16_f32 v2, v2, v3
	v_add_f32_e32 v20, 1.0, v20
	v_add_f32_e32 v21, 1.0, v21
	v_rcp_f32_e32 v20, v20
	v_rcp_f32_e32 v21, v21
	s_nop 0
	v_pk_mul_f32 v[18:19], v[20:21], v[18:19]
	s_nop 0
	v_pk_mul_f32 v[4:5], v[4:5], v[18:19]
	v_xad_u32 v20, v73, s78, v69
	v_cvt_pk_bf16_f32 v3, v4, v5
	ds_write_b64 v24, v[2:3]
	ds_read_b64 v[2:3], v20
	s_waitcnt lgkmcnt(0)
	v_lshlrev_b32_e32 v4, 16, v2
	v_and_b32_e32 v5, 0xffff0000, v2
	v_mul_f32_e32 v2, 0xbfb8aa3b, v4
	v_exp_f32_e32 v2, v2
	s_nop 0
	v_add_f32_e32 v2, 1.0, v2
	v_rcp_f32_e32 v18, v2
	v_mul_f32_e32 v2, 0xbfb8aa3b, v5
	v_exp_f32_e32 v2, v2
	s_nop 0
	v_add_f32_e32 v2, 1.0, v2
	v_rcp_f32_e32 v19, v2
	v_lshlrev_b32_e32 v2, 16, v3
	v_and_b32_e32 v3, 0xffff0000, v3
	v_pk_mul_f32 v[4:5], v[18:19], v[4:5]
	s_nop 0
	v_pk_mul_f32 v[4:5], v[6:7], v[4:5]
	v_mul_f32_e32 v6, 0xbfb8aa3b, v2
	v_mul_f32_e32 v7, 0xbfb8aa3b, v3
	v_exp_f32_e32 v6, v6
	v_exp_f32_e32 v7, v7
	v_cvt_pk_bf16_f32 v4, v4, v5
	v_xad_u32 v18, v73, s7, v69
	v_add_f32_e32 v6, 1.0, v6
	v_add_f32_e32 v7, 1.0, v7
	v_rcp_f32_e32 v6, v6
	v_rcp_f32_e32 v7, v7
	s_movk_i32 s7, 0xf0
	v_pk_mul_f32 v[2:3], v[6:7], v[2:3]
	s_nop 0
	v_pk_mul_f32 v[2:3], v[8:9], v[2:3]
	v_pk_mul_f32 v[8:9], v[10:11], v[68:69] op_sel_hi:[1,0]
	v_cvt_pk_bf16_f32 v5, v2, v3
	ds_write_b64 v20, v[4:5]
	ds_read_b64 v[2:3], v18
	v_xad_u32 v10, v73, s7, v69
	s_waitcnt lgkmcnt(0)
	v_lshlrev_b32_e32 v4, 16, v2
	v_and_b32_e32 v5, 0xffff0000, v2
	v_mul_f32_e32 v2, 0xbfb8aa3b, v4
	v_exp_f32_e32 v2, v2
	s_nop 0
	v_add_f32_e32 v2, 1.0, v2
	v_rcp_f32_e32 v6, v2
	v_mul_f32_e32 v2, 0xbfb8aa3b, v5
	v_exp_f32_e32 v2, v2
	s_nop 0
	v_add_f32_e32 v2, 1.0, v2
	v_rcp_f32_e32 v7, v2
	v_lshlrev_b32_e32 v2, 16, v3
	v_and_b32_e32 v3, 0xffff0000, v3
	v_pk_mul_f32 v[4:5], v[6:7], v[4:5]
	v_mul_f32_e32 v6, 0xbfb8aa3b, v2
	v_mul_f32_e32 v7, 0xbfb8aa3b, v3
	v_exp_f32_e32 v6, v6
	v_exp_f32_e32 v7, v7
	v_pk_mul_f32 v[4:5], v[8:9], v[4:5]
	v_pk_mul_f32 v[8:9], v[12:13], v[68:69] op_sel_hi:[1,0]
	v_add_f32_e32 v6, 1.0, v6
	v_add_f32_e32 v7, 1.0, v7
	v_rcp_f32_e32 v6, v6
	v_rcp_f32_e32 v7, v7
	v_cvt_pk_bf16_f32 v4, v4, v5
	v_pk_mul_f32 v[2:3], v[6:7], v[2:3]
	s_nop 0
	v_pk_mul_f32 v[2:3], v[8:9], v[2:3]
	v_pk_mul_f32 v[8:9], v[14:15], v[68:69] op_sel_hi:[1,0]
	v_cvt_pk_bf16_f32 v5, v2, v3
	ds_write_b64 v18, v[4:5]
	ds_read_b64 v[2:3], v10
	s_waitcnt lgkmcnt(0)
	v_lshlrev_b32_e32 v4, 16, v2
	v_and_b32_e32 v5, 0xffff0000, v2
	v_mul_f32_e32 v2, 0xbfb8aa3b, v4
	v_exp_f32_e32 v2, v2
	s_nop 0
	v_add_f32_e32 v2, 1.0, v2
	v_rcp_f32_e32 v6, v2
	v_mul_f32_e32 v2, 0xbfb8aa3b, v5
	v_exp_f32_e32 v2, v2
	s_nop 0
	v_add_f32_e32 v2, 1.0, v2
	v_rcp_f32_e32 v7, v2
	v_lshlrev_b32_e32 v2, 16, v3
	v_and_b32_e32 v3, 0xffff0000, v3
	v_pk_mul_f32 v[4:5], v[6:7], v[4:5]
	v_mul_f32_e32 v6, 0xbfb8aa3b, v2
	v_mul_f32_e32 v7, 0xbfb8aa3b, v3
	v_exp_f32_e32 v6, v6
	v_exp_f32_e32 v7, v7
	v_pk_mul_f32 v[4:5], v[8:9], v[4:5]
	v_pk_mul_f32 v[8:9], v[16:17], v[68:69] op_sel_hi:[1,0]
	v_add_f32_e32 v6, 1.0, v6
	v_add_f32_e32 v7, 1.0, v7
	v_rcp_f32_e32 v6, v6
	v_rcp_f32_e32 v7, v7
	v_cvt_pk_bf16_f32 v4, v4, v5
	v_pk_mul_f32 v[2:3], v[6:7], v[2:3]
	s_nop 0
	v_pk_mul_f32 v[2:3], v[8:9], v[2:3]
	s_nop 0
	v_cvt_pk_bf16_f32 v5, v2, v3
	ds_write_b64 v10, v[4:5]
	v_lshl_add_u64 v[2:3], v[66:67], 1, s[4:5]
	v_add_u32_e32 v4, s6, v70
	v_add3_u32 v5, v71, v72, 0
	s_mov_b32 s4, 0
	s_waitcnt lgkmcnt(0)
	s_barrier
